# nt on the read-once epilogue loads of both P4 GEMMs as well
# baseline (speedup 1.0000x reference)
; __device__ __forceinline__ unsigned cvt_pk_bf16(float lo, float hi) { unsigned r; asm volatile("v_cvt_pk_bf16_f32 %0, %1, %2" : "=v"(r) : "v"(lo), "v"(hi)); return r; }
;     __device__ __forceinline__ void operator()(const f32x4 (&acc)[2][2][4][2], const pg8::Unit& u, int wr, int wc, int fr, int fq) const {
;     ...
;                     if (MODE == 0) { const u32x4 o = *(const u32x4*)(O + off);
;                         r[0] = bflo(o.x) * v0[0]; r[1] = bfhi(o.x) * v0[1]; r[2] = bflo(o.y) * v0[2]; r[3] = bfhi(o.y) * v0[3];
;                         r[4] = bflo(o.z) * v1[0]; r[5] = bfhi(o.z) * v1[1]; r[6] = bflo(o.w) * v1[2]; r[7] = bfhi(o.w) * v1[3]; }
;                     else { const u32x4 gq = *(const u32x4*)(G + off);
;                         r[0] = bflo(gq.x) * v0[0]; r[1] = bfhi(gq.x) * v0[1]; r[2] = bflo(gq.y) * v0[2]; r[3] = bfhi(gq.y) * v0[3];
;                         r[4] = bflo(gq.z) * v1[0]; r[5] = bfhi(gq.z) * v1[1]; r[6] = bflo(gq.w) * v1[2]; r[7] = bfhi(gq.w) * v1[3];
;                         if (MODE == 2) { const u32x4 o = *(const u32x4*)(O + off);
;                             r[0] += bflo(o.x); r[1] += bfhi(o.x); r[2] += bflo(o.y); r[3] += bfhi(o.y); r[4] += bflo(o.z); r[5] += bfhi(o.z); r[6] += bflo(o.w); r[7] += bfhi(o.w); } }
;                     u32x4 w; w.x = cvt_pk_bf16(r[0], r[1]); w.y = cvt_pk_bf16(r[2], r[3]); w.z = cvt_pk_bf16(r[4], r[5]); w.w = cvt_pk_bf16(r[6], r[7]);
;                     *(u32x4*)(O + off) = w; } }
.LBB0_1003:
	v_lshl_add_u32 v148, s68, 8, v155
	v_lshl_or_b32 v146, s80, 8, v160
	v_ashrrev_i32_e32 v149, 31, v148
	v_ashrrev_i32_e32 v147, 31, v146
	v_lshlrev_b64 v[144:145], 11, v[148:149]
	v_lshl_add_u64 v[144:145], v[144:145], 0, v[146:147]
	v_lshlrev_b64 v[144:145], 1, v[144:145]
	v_lshl_add_u64 v[164:165], s[42:43], 0, v[144:145]
	global_load_dwordx4 v[164:167], v[164:165], off nt
	v_lshl_add_u64 v[168:169], s[24:25], 0, v[144:145]
	v_or_b32_e32 v170, 0x100, v144
	v_mov_b32_e32 v171, v145
	v_lshl_add_u64 v[172:173], s[42:43], 0, v[170:171]
	s_andn2_b64 vcc, exec, s[0:1]
	s_mov_b64 s[0:1], -1
	s_waitcnt vmcnt(0)
	v_lshlrev_b32_e32 v176, 16, v167
	v_and_b32_e32 v167, 0xffff0000, v167
	v_lshlrev_b32_e32 v149, 16, v164
	v_and_b32_e32 v164, 0xffff0000, v164
	v_lshlrev_b32_e32 v174, 16, v165
	v_and_b32_e32 v165, 0xffff0000, v165
	v_lshlrev_b32_e32 v175, 16, v166
	v_and_b32_e32 v166, 0xffff0000, v166
	v_mul_f32_e32 v123, v123, v167
	v_mul_f32_e32 v124, v124, v149
	v_mul_f32_e32 v125, v125, v164
	v_mul_f32_e32 v126, v126, v174
	v_mul_f32_e32 v127, v127, v165
	v_mul_f32_e32 v149, v120, v175
	v_mul_f32_e32 v164, v121, v166
	v_mul_f32_e32 v165, v122, v176
	v_cvt_pk_bf16_f32 v120, v124, v125
	v_cvt_pk_bf16_f32 v121, v126, v127
	v_cvt_pk_bf16_f32 v122, v149, v164
	v_cvt_pk_bf16_f32 v123, v165, v123
	global_store_dwordx4 v[168:169], v[120:123], off
	global_load_dwordx4 v[120:123], v[172:173], off nt
	v_or_b32_e32 v124, 16, v148
	v_ashrrev_i32_e32 v125, 31, v124
	v_lshlrev_b64 v[124:125], 11, v[124:125]
	v_lshl_add_u64 v[124:125], v[124:125], 0, v[146:147]
	v_lshlrev_b64 v[124:125], 1, v[124:125]
	v_lshl_add_u64 v[126:127], s[24:25], 0, v[170:171]
	v_lshl_add_u64 v[164:165], s[42:43], 0, v[124:125]
	s_waitcnt vmcnt(0)
	v_lshlrev_b32_e32 v168, 16, v123
	v_and_b32_e32 v123, 0xffff0000, v123
	v_lshlrev_b32_e32 v149, 16, v120
	v_and_b32_e32 v120, 0xffff0000, v120
	v_lshlrev_b32_e32 v166, 16, v121
	v_and_b32_e32 v121, 0xffff0000, v121
	v_lshlrev_b32_e32 v167, 16, v122
	v_and_b32_e32 v122, 0xffff0000, v122
	v_mul_f32_e32 v115, v115, v123
	v_mul_f32_e32 v116, v116, v149
	v_mul_f32_e32 v117, v117, v120
	v_mul_f32_e32 v118, v118, v166
	v_mul_f32_e32 v119, v119, v121
	v_mul_f32_e32 v120, v112, v167
	v_mul_f32_e32 v121, v113, v122
	v_mul_f32_e32 v122, v114, v168
	v_cvt_pk_bf16_f32 v112, v116, v117
	v_cvt_pk_bf16_f32 v113, v118, v119
	v_cvt_pk_bf16_f32 v114, v120, v121
	v_cvt_pk_bf16_f32 v115, v122, v115
	global_store_dwordx4 v[126:127], v[112:115], off
	global_load_dwordx4 v[112:115], v[164:165], off nt
	v_lshl_add_u64 v[116:117], s[24:25], 0, v[124:125]
	v_or_b32_e32 v124, 0x100, v124
	v_lshl_add_u64 v[118:119], s[42:43], 0, v[124:125]
	s_waitcnt vmcnt(0)
	v_lshlrev_b32_e32 v123, 16, v115
	v_and_b32_e32 v115, 0xffff0000, v115
	v_lshlrev_b32_e32 v120, 16, v112
	v_and_b32_e32 v112, 0xffff0000, v112
	v_lshlrev_b32_e32 v121, 16, v113
	v_and_b32_e32 v113, 0xffff0000, v113
	v_lshlrev_b32_e32 v122, 16, v114
	v_and_b32_e32 v114, 0xffff0000, v114
	v_mul_f32_e32 v107, v107, v115
	v_mul_f32_e32 v108, v108, v120
	v_mul_f32_e32 v109, v109, v112
	v_mul_f32_e32 v110, v110, v121
	v_mul_f32_e32 v111, v111, v113
	v_mul_f32_e32 v112, v104, v122
	v_mul_f32_e32 v113, v105, v114
	v_mul_f32_e32 v114, v106, v123
	v_cvt_pk_bf16_f32 v104, v108, v109
	v_cvt_pk_bf16_f32 v105, v110, v111
	v_cvt_pk_bf16_f32 v106, v112, v113
	v_cvt_pk_bf16_f32 v107, v114, v107
	global_store_dwordx4 v[116:117], v[104:107], off
	global_load_dwordx4 v[104:107], v[118:119], off nt
	v_or_b32_e32 v108, 32, v148
	v_ashrrev_i32_e32 v109, 31, v108
	v_lshlrev_b64 v[108:109], 11, v[108:109]
	v_lshl_add_u64 v[108:109], v[108:109], 0, v[146:147]
	v_lshlrev_b64 v[108:109], 1, v[108:109]
	v_lshl_add_u64 v[112:113], s[24:25], 0, v[124:125]
	v_lshl_add_u64 v[110:111], s[42:43], 0, v[108:109]
	s_waitcnt vmcnt(0)
	v_lshlrev_b32_e32 v117, 16, v107
	v_and_b32_e32 v107, 0xffff0000, v107
	v_lshlrev_b32_e32 v114, 16, v104
	v_and_b32_e32 v104, 0xffff0000, v104
	v_lshlrev_b32_e32 v115, 16, v105
	v_and_b32_e32 v105, 0xffff0000, v105
	v_lshlrev_b32_e32 v116, 16, v106
	v_and_b32_e32 v106, 0xffff0000, v106
	v_mul_f32_e32 v99, v99, v107
	v_mul_f32_e32 v100, v100, v114
	v_mul_f32_e32 v101, v101, v104
	v_mul_f32_e32 v102, v102, v115
	v_mul_f32_e32 v103, v103, v105
	v_mul_f32_e32 v104, v96, v116
	v_mul_f32_e32 v105, v97, v106
	v_mul_f32_e32 v106, v98, v117
	v_cvt_pk_bf16_f32 v96, v100, v101
	v_cvt_pk_bf16_f32 v97, v102, v103
	v_cvt_pk_bf16_f32 v98, v104, v105
	v_cvt_pk_bf16_f32 v99, v106, v99
	global_store_dwordx4 v[112:113], v[96:99], off
	global_load_dwordx4 v[96:99], v[110:111], off nt
	v_lshl_add_u64 v[100:101], s[24:25], 0, v[108:109]
	v_or_b32_e32 v108, 0x100, v108
	v_lshl_add_u64 v[102:103], s[42:43], 0, v[108:109]
	s_waitcnt vmcnt(0)
	v_lshlrev_b32_e32 v107, 16, v99
	v_and_b32_e32 v99, 0xffff0000, v99
	v_lshlrev_b32_e32 v104, 16, v96
	v_and_b32_e32 v96, 0xffff0000, v96
	v_lshlrev_b32_e32 v105, 16, v97
	v_and_b32_e32 v97, 0xffff0000, v97
	v_lshlrev_b32_e32 v106, 16, v98
	v_and_b32_e32 v98, 0xffff0000, v98
	v_mul_f32_e32 v91, v91, v99
	v_mul_f32_e32 v92, v92, v104
	v_mul_f32_e32 v93, v93, v96
	v_mul_f32_e32 v94, v94, v105
	v_mul_f32_e32 v95, v95, v97
	v_mul_f32_e32 v96, v88, v106
	v_mul_f32_e32 v97, v89, v98
	v_mul_f32_e32 v98, v90, v107
	v_cvt_pk_bf16_f32 v88, v92, v93
	v_cvt_pk_bf16_f32 v89, v94, v95
	v_cvt_pk_bf16_f32 v90, v96, v97
	v_cvt_pk_bf16_f32 v91, v98, v91
	global_store_dwordx4 v[100:101], v[88:91], off
	global_load_dwordx4 v[88:91], v[102:103], off nt
	v_or_b32_e32 v92, 48, v148
	v_ashrrev_i32_e32 v93, 31, v92
	v_lshlrev_b64 v[92:93], 11, v[92:93]
	v_lshl_add_u64 v[92:93], v[92:93], 0, v[146:147]
	v_lshlrev_b64 v[92:93], 1, v[92:93]
	v_lshl_add_u64 v[96:97], s[24:25], 0, v[108:109]
	v_lshl_add_u64 v[94:95], s[42:43], 0, v[92:93]
	s_waitcnt vmcnt(0)
; __device__ __forceinline__ unsigned cvt_pk_bf16(float lo, float hi) { unsigned r; asm volatile("v_cvt_pk_bf16_f32 %0, %1, %2" : "=v"(r) : "v"(lo), "v"(hi)); return r; }
;     __device__ __forceinline__ void operator()(const f32x4 (&acc)[2][2][4][2], const pg8::Unit& u, int wr, int wc, int fr, int fq) const {
;     ...
;                     if (MODE == 0) { const u32x4 o = *(const u32x4*)(O + off);
;                         r[0] = bflo(o.x) * v0[0]; r[1] = bfhi(o.x) * v0[1]; r[2] = bflo(o.y) * v0[2]; r[3] = bfhi(o.y) * v0[3];
;                         r[4] = bflo(o.z) * v1[0]; r[5] = bfhi(o.z) * v1[1]; r[6] = bflo(o.w) * v1[2]; r[7] = bfhi(o.w) * v1[3]; }
;                     else { const u32x4 gq = *(const u32x4*)(G + off);
;                         r[0] = bflo(gq.x) * v0[0]; r[1] = bfhi(gq.x) * v0[1]; r[2] = bflo(gq.y) * v0[2]; r[3] = bfhi(gq.y) * v0[3];
;                         r[4] = bflo(gq.z) * v1[0]; r[5] = bfhi(gq.z) * v1[1]; r[6] = bflo(gq.w) * v1[2]; r[7] = bfhi(gq.w) * v1[3];
;                         if (MODE == 2) { const u32x4 o = *(const u32x4*)(O + off);
;                             r[0] += bflo(o.x); r[1] += bfhi(o.x); r[2] += bflo(o.y); r[3] += bfhi(o.y); r[4] += bflo(o.z); r[5] += bfhi(o.z); r[6] += bflo(o.w); r[7] += bfhi(o.w); } }
;                     u32x4 w; w.x = cvt_pk_bf16(r[0], r[1]); w.y = cvt_pk_bf16(r[2], r[3]); w.z = cvt_pk_bf16(r[4], r[5]); w.w = cvt_pk_bf16(r[6], r[7]);
;                     *(u32x4*)(O + off) = w; } }
	v_lshlrev_b32_e32 v101, 16, v91
	v_and_b32_e32 v91, 0xffff0000, v91
	v_lshlrev_b32_e32 v98, 16, v88
	v_and_b32_e32 v88, 0xffff0000, v88
	v_lshlrev_b32_e32 v99, 16, v89
	v_and_b32_e32 v89, 0xffff0000, v89
	v_lshlrev_b32_e32 v100, 16, v90
	v_and_b32_e32 v90, 0xffff0000, v90
	v_mul_f32_e32 v83, v83, v91
	v_mul_f32_e32 v84, v84, v98
	v_mul_f32_e32 v85, v85, v88
	v_mul_f32_e32 v86, v86, v99
	v_mul_f32_e32 v87, v87, v89
	v_mul_f32_e32 v88, v80, v100
	v_mul_f32_e32 v89, v81, v90
	v_mul_f32_e32 v90, v82, v101
	v_cvt_pk_bf16_f32 v80, v84, v85
	v_cvt_pk_bf16_f32 v81, v86, v87
	v_cvt_pk_bf16_f32 v82, v88, v89
	v_cvt_pk_bf16_f32 v83, v90, v83
	global_store_dwordx4 v[96:97], v[80:83], off
	global_load_dwordx4 v[80:83], v[94:95], off nt
	v_lshl_add_u64 v[84:85], s[24:25], 0, v[92:93]
	v_or_b32_e32 v92, 0x100, v92
	v_lshl_add_u64 v[86:87], s[42:43], 0, v[92:93]
	s_waitcnt vmcnt(0)
	v_lshlrev_b32_e32 v91, 16, v83
	v_and_b32_e32 v83, 0xffff0000, v83
	v_lshlrev_b32_e32 v88, 16, v80
	v_and_b32_e32 v80, 0xffff0000, v80
	v_lshlrev_b32_e32 v89, 16, v81
	v_and_b32_e32 v81, 0xffff0000, v81
	v_lshlrev_b32_e32 v90, 16, v82
	v_and_b32_e32 v82, 0xffff0000, v82
	v_mul_f32_e32 v75, v75, v83
	v_mul_f32_e32 v76, v76, v88
	v_mul_f32_e32 v77, v77, v80
	v_mul_f32_e32 v78, v78, v89
	v_mul_f32_e32 v79, v79, v81
	v_mul_f32_e32 v80, v72, v90
	v_mul_f32_e32 v81, v73, v82
	v_mul_f32_e32 v82, v74, v91
	v_cvt_pk_bf16_f32 v72, v76, v77
	v_cvt_pk_bf16_f32 v73, v78, v79
	v_cvt_pk_bf16_f32 v74, v80, v81
	v_cvt_pk_bf16_f32 v75, v82, v75
	global_store_dwordx4 v[84:85], v[72:75], off
	global_load_dwordx4 v[72:75], v[86:87], off nt
	v_lshl_add_u64 v[76:77], v[144:145], 0, s[8:9]
	v_lshl_add_u64 v[80:81], s[24:25], 0, v[92:93]
	v_lshl_add_u64 v[78:79], s[42:43], 0, v[76:77]
	s_waitcnt vmcnt(0)
	v_lshlrev_b32_e32 v85, 16, v75
	v_and_b32_e32 v75, 0xffff0000, v75
	v_lshlrev_b32_e32 v82, 16, v72
	v_and_b32_e32 v72, 0xffff0000, v72
	v_lshlrev_b32_e32 v83, 16, v73
	v_and_b32_e32 v73, 0xffff0000, v73
	v_lshlrev_b32_e32 v84, 16, v74
	v_and_b32_e32 v74, 0xffff0000, v74
	v_mul_f32_e32 v67, v67, v75
	v_mul_f32_e32 v68, v68, v82
	v_mul_f32_e32 v69, v69, v72
	v_mul_f32_e32 v70, v70, v83
	v_mul_f32_e32 v71, v71, v73
	v_mul_f32_e32 v72, v64, v84
	v_mul_f32_e32 v73, v65, v74
	v_mul_f32_e32 v74, v66, v85
	v_cvt_pk_bf16_f32 v64, v68, v69
	v_cvt_pk_bf16_f32 v65, v70, v71
	v_cvt_pk_bf16_f32 v66, v72, v73
	v_cvt_pk_bf16_f32 v67, v74, v67
	global_store_dwordx4 v[80:81], v[64:67], off
	global_load_dwordx4 v[64:67], v[78:79], off nt
	v_lshl_add_u64 v[70:71], s[24:25], 0, v[76:77]
	v_lshl_add_u64 v[68:69], v[144:145], 0, s[16:17]
	v_lshl_add_u64 v[72:73], s[42:43], 0, v[68:69]
	s_waitcnt vmcnt(0)
	v_lshlrev_b32_e32 v77, 16, v67
	v_and_b32_e32 v67, 0xffff0000, v67
	v_lshlrev_b32_e32 v74, 16, v64
	v_and_b32_e32 v64, 0xffff0000, v64
	v_lshlrev_b32_e32 v75, 16, v65
	v_and_b32_e32 v65, 0xffff0000, v65
	v_lshlrev_b32_e32 v76, 16, v66
	v_and_b32_e32 v66, 0xffff0000, v66
	v_mul_f32_e32 v59, v59, v67
	v_mul_f32_e32 v60, v60, v74
	v_mul_f32_e32 v61, v61, v64
	v_mul_f32_e32 v62, v62, v75
	v_mul_f32_e32 v63, v63, v65
	v_mul_f32_e32 v64, v56, v76
	v_mul_f32_e32 v65, v57, v66
	v_mul_f32_e32 v66, v58, v77
	v_cvt_pk_bf16_f32 v56, v60, v61
	v_cvt_pk_bf16_f32 v57, v62, v63
	v_cvt_pk_bf16_f32 v58, v64, v65
	v_cvt_pk_bf16_f32 v59, v66, v59
	global_store_dwordx4 v[70:71], v[56:59], off
	global_load_dwordx4 v[56:59], v[72:73], off nt
	v_lshl_add_u64 v[62:63], s[24:25], 0, v[68:69]
	v_lshl_add_u64 v[60:61], v[144:145], 0, s[18:19]
	v_lshl_add_u64 v[64:65], s[42:43], 0, v[60:61]
	s_waitcnt vmcnt(0)
	v_lshlrev_b32_e32 v69, 16, v59
	v_and_b32_e32 v59, 0xffff0000, v59
	v_lshlrev_b32_e32 v66, 16, v56
	v_and_b32_e32 v56, 0xffff0000, v56
	v_lshlrev_b32_e32 v67, 16, v57
	v_and_b32_e32 v57, 0xffff0000, v57
	v_lshlrev_b32_e32 v68, 16, v58
	v_and_b32_e32 v58, 0xffff0000, v58
	v_mul_f32_e32 v51, v51, v59
	v_mul_f32_e32 v52, v52, v66
	v_mul_f32_e32 v53, v53, v56
	v_mul_f32_e32 v54, v54, v67
	v_mul_f32_e32 v55, v55, v57
	v_mul_f32_e32 v56, v48, v68
	v_mul_f32_e32 v57, v49, v58
	v_mul_f32_e32 v58, v50, v69
	v_cvt_pk_bf16_f32 v48, v52, v53
	v_cvt_pk_bf16_f32 v49, v54, v55
	v_cvt_pk_bf16_f32 v50, v56, v57
	v_cvt_pk_bf16_f32 v51, v58, v51
	global_store_dwordx4 v[62:63], v[48:51], off
	global_load_dwordx4 v[48:51], v[64:65], off nt
	v_lshl_add_u64 v[54:55], s[24:25], 0, v[60:61]
	v_lshl_add_u64 v[52:53], v[144:145], 0, s[20:21]
	v_lshl_add_u64 v[56:57], s[42:43], 0, v[52:53]
	s_waitcnt vmcnt(0)
; __device__ __forceinline__ unsigned cvt_pk_bf16(float lo, float hi) { unsigned r; asm volatile("v_cvt_pk_bf16_f32 %0, %1, %2" : "=v"(r) : "v"(lo), "v"(hi)); return r; }
;     __device__ __forceinline__ void operator()(const f32x4 (&acc)[2][2][4][2], const pg8::Unit& u, int wr, int wc, int fr, int fq) const {
;     ...
;                     if (MODE == 0) { const u32x4 o = *(const u32x4*)(O + off);
;                         r[0] = bflo(o.x) * v0[0]; r[1] = bfhi(o.x) * v0[1]; r[2] = bflo(o.y) * v0[2]; r[3] = bfhi(o.y) * v0[3];
;                         r[4] = bflo(o.z) * v1[0]; r[5] = bfhi(o.z) * v1[1]; r[6] = bflo(o.w) * v1[2]; r[7] = bfhi(o.w) * v1[3]; }
;                     else { const u32x4 gq = *(const u32x4*)(G + off);
;                         r[0] = bflo(gq.x) * v0[0]; r[1] = bfhi(gq.x) * v0[1]; r[2] = bflo(gq.y) * v0[2]; r[3] = bfhi(gq.y) * v0[3];
;                         r[4] = bflo(gq.z) * v1[0]; r[5] = bfhi(gq.z) * v1[1]; r[6] = bflo(gq.w) * v1[2]; r[7] = bfhi(gq.w) * v1[3];
;                         if (MODE == 2) { const u32x4 o = *(const u32x4*)(O + off);
;                             r[0] += bflo(o.x); r[1] += bfhi(o.x); r[2] += bflo(o.y); r[3] += bfhi(o.y); r[4] += bflo(o.z); r[5] += bfhi(o.z); r[6] += bflo(o.w); r[7] += bfhi(o.w); } }
;                     u32x4 w; w.x = cvt_pk_bf16(r[0], r[1]); w.y = cvt_pk_bf16(r[2], r[3]); w.z = cvt_pk_bf16(r[4], r[5]); w.w = cvt_pk_bf16(r[6], r[7]);
;                     *(u32x4*)(O + off) = w; } }
	v_lshlrev_b32_e32 v61, 16, v51
	v_and_b32_e32 v51, 0xffff0000, v51
	v_lshlrev_b32_e32 v58, 16, v48
	v_and_b32_e32 v48, 0xffff0000, v48
	v_lshlrev_b32_e32 v59, 16, v49
	v_and_b32_e32 v49, 0xffff0000, v49
	v_lshlrev_b32_e32 v60, 16, v50
	v_and_b32_e32 v50, 0xffff0000, v50
	v_mul_f32_e32 v43, v43, v51
	v_mul_f32_e32 v44, v44, v58
	v_mul_f32_e32 v45, v45, v48
	v_mul_f32_e32 v46, v46, v59
	v_mul_f32_e32 v47, v47, v49
	v_mul_f32_e32 v48, v40, v60
	v_mul_f32_e32 v49, v41, v50
	v_mul_f32_e32 v50, v42, v61
	v_cvt_pk_bf16_f32 v40, v44, v45
	v_cvt_pk_bf16_f32 v41, v46, v47
	v_cvt_pk_bf16_f32 v42, v48, v49
	v_cvt_pk_bf16_f32 v43, v50, v43
	global_store_dwordx4 v[54:55], v[40:43], off
	global_load_dwordx4 v[40:43], v[56:57], off nt
	v_lshl_add_u64 v[46:47], s[24:25], 0, v[52:53]
	v_lshl_add_u64 v[44:45], v[144:145], 0, s[22:23]
	v_lshl_add_u64 v[48:49], s[42:43], 0, v[44:45]
	s_waitcnt vmcnt(0)
	v_lshlrev_b32_e32 v53, 16, v43
	v_and_b32_e32 v43, 0xffff0000, v43
	v_lshlrev_b32_e32 v50, 16, v40
	v_and_b32_e32 v40, 0xffff0000, v40
	v_lshlrev_b32_e32 v51, 16, v41
	v_and_b32_e32 v41, 0xffff0000, v41
	v_lshlrev_b32_e32 v52, 16, v42
	v_and_b32_e32 v42, 0xffff0000, v42
	v_mul_f32_e32 v35, v35, v43
	v_mul_f32_e32 v36, v36, v50
	v_mul_f32_e32 v37, v37, v40
	v_mul_f32_e32 v38, v38, v51
	v_mul_f32_e32 v39, v39, v41
	v_mul_f32_e32 v40, v32, v52
	v_mul_f32_e32 v41, v33, v42
	v_mul_f32_e32 v42, v34, v53
	v_cvt_pk_bf16_f32 v32, v36, v37
	v_cvt_pk_bf16_f32 v33, v38, v39
	v_cvt_pk_bf16_f32 v34, v40, v41
	v_cvt_pk_bf16_f32 v35, v42, v35
	global_store_dwordx4 v[46:47], v[32:35], off
	global_load_dwordx4 v[32:35], v[48:49], off nt
	v_lshl_add_u64 v[38:39], s[24:25], 0, v[44:45]
	v_lshl_add_u64 v[36:37], v[144:145], 0, s[40:41]
	v_lshl_add_u64 v[40:41], s[42:43], 0, v[36:37]
	s_waitcnt vmcnt(0)
	v_lshlrev_b32_e32 v45, 16, v35
	v_and_b32_e32 v35, 0xffff0000, v35
	v_lshlrev_b32_e32 v42, 16, v32
	v_and_b32_e32 v32, 0xffff0000, v32
	v_lshlrev_b32_e32 v43, 16, v33
	v_and_b32_e32 v33, 0xffff0000, v33
	v_lshlrev_b32_e32 v44, 16, v34
	v_and_b32_e32 v34, 0xffff0000, v34
	v_mul_f32_e32 v27, v27, v35
	v_mul_f32_e32 v28, v28, v42
	v_mul_f32_e32 v29, v29, v32
	v_mul_f32_e32 v30, v30, v43
	v_mul_f32_e32 v31, v31, v33
	v_mul_f32_e32 v32, v24, v44
	v_mul_f32_e32 v33, v25, v34
	v_mul_f32_e32 v34, v26, v45
	v_cvt_pk_bf16_f32 v24, v28, v29
	v_cvt_pk_bf16_f32 v25, v30, v31
	v_cvt_pk_bf16_f32 v26, v32, v33
	v_cvt_pk_bf16_f32 v27, v34, v27
	global_store_dwordx4 v[38:39], v[24:27], off
	global_load_dwordx4 v[24:27], v[40:41], off nt
	v_lshl_add_u64 v[30:31], s[24:25], 0, v[36:37]
	v_lshl_add_u64 v[28:29], v[144:145], 0, s[44:45]
	v_lshl_add_u64 v[32:33], s[42:43], 0, v[28:29]
	s_waitcnt vmcnt(0)
	v_lshlrev_b32_e32 v37, 16, v27
	v_and_b32_e32 v27, 0xffff0000, v27
	v_lshlrev_b32_e32 v34, 16, v24
	v_and_b32_e32 v24, 0xffff0000, v24
	v_lshlrev_b32_e32 v35, 16, v25
	v_and_b32_e32 v25, 0xffff0000, v25
	v_lshlrev_b32_e32 v36, 16, v26
	v_and_b32_e32 v26, 0xffff0000, v26
	v_mul_f32_e32 v19, v19, v27
	v_mul_f32_e32 v20, v20, v34
	v_mul_f32_e32 v21, v21, v24
	v_mul_f32_e32 v22, v22, v35
	v_mul_f32_e32 v23, v23, v25
	v_mul_f32_e32 v24, v16, v36
	v_mul_f32_e32 v25, v17, v26
	v_mul_f32_e32 v26, v18, v37
	v_cvt_pk_bf16_f32 v16, v20, v21
	v_cvt_pk_bf16_f32 v17, v22, v23
	v_cvt_pk_bf16_f32 v18, v24, v25
	v_cvt_pk_bf16_f32 v19, v26, v19
	global_store_dwordx4 v[30:31], v[16:19], off
	global_load_dwordx4 v[16:19], v[32:33], off nt
	v_lshl_add_u64 v[22:23], s[24:25], 0, v[28:29]
	v_lshl_add_u64 v[20:21], v[144:145], 0, s[46:47]
	v_lshl_add_u64 v[24:25], s[42:43], 0, v[20:21]
	s_waitcnt vmcnt(0)
	v_lshlrev_b32_e32 v29, 16, v19
	v_and_b32_e32 v19, 0xffff0000, v19
	v_lshlrev_b32_e32 v26, 16, v16
	v_and_b32_e32 v16, 0xffff0000, v16
	v_lshlrev_b32_e32 v27, 16, v17
	v_and_b32_e32 v17, 0xffff0000, v17
	v_lshlrev_b32_e32 v28, 16, v18
	v_and_b32_e32 v18, 0xffff0000, v18
	v_mul_f32_e32 v11, v11, v19
	v_mul_f32_e32 v12, v12, v26
	v_mul_f32_e32 v13, v13, v16
	v_mul_f32_e32 v14, v14, v27
	v_mul_f32_e32 v15, v15, v17
	v_mul_f32_e32 v16, v8, v28
	v_mul_f32_e32 v17, v9, v18
	v_mul_f32_e32 v18, v10, v29
	v_cvt_pk_bf16_f32 v8, v12, v13
	v_cvt_pk_bf16_f32 v9, v14, v15
	v_cvt_pk_bf16_f32 v10, v16, v17
	v_cvt_pk_bf16_f32 v11, v18, v11
	global_store_dwordx4 v[22:23], v[8:11], off
	global_load_dwordx4 v[8:11], v[24:25], off nt
	v_lshl_add_u64 v[12:13], s[24:25], 0, v[20:21]
	s_waitcnt vmcnt(0)
	v_lshlrev_b32_e32 v17, 16, v11
	v_and_b32_e32 v11, 0xffff0000, v11
	v_lshlrev_b32_e32 v14, 16, v8
	v_and_b32_e32 v8, 0xffff0000, v8
	v_lshlrev_b32_e32 v15, 16, v9
	v_and_b32_e32 v9, 0xffff0000, v9
	v_lshlrev_b32_e32 v16, 16, v10
	v_and_b32_e32 v10, 0xffff0000, v10
	v_mul_f32_e32 v3, v3, v11
	v_mul_f32_e32 v4, v4, v14
	v_mul_f32_e32 v5, v5, v8
	v_mul_f32_e32 v6, v6, v15
	v_mul_f32_e32 v7, v7, v9
	v_mul_f32_e32 v8, v0, v16
	v_mul_f32_e32 v9, v1, v10
	v_mul_f32_e32 v10, v2, v17
	v_cvt_pk_bf16_f32 v0, v4, v5
	v_cvt_pk_bf16_f32 v1, v6, v7
	v_cvt_pk_bf16_f32 v2, v8, v9
	v_cvt_pk_bf16_f32 v3, v10, v3
	global_store_dwordx4 v[12:13], v[0:3], off
	s_cbranch_vccnz .LBB0_992
	s_andn2_b64 vcc, exec, s[10:11]
	s_cbranch_vccnz .LBB0_991
	s_barrier
	s_branch .LBB0_991

; __device__ __forceinline__ unsigned cvt_pk_bf16(float lo, float hi) { unsigned r; asm volatile("v_cvt_pk_bf16_f32 %0, %1, %2" : "=v"(r) : "v"(lo), "v"(hi)); return r; }
;     __device__ __forceinline__ void operator()(const f32x4 (&acc)[2][2][4][2], const pg8::Unit& u, int wr, int wc, int fr, int fq) const {
;     ...
;                     else { const u32x4 gq = *(const u32x4*)(G + off);
;                         r[0] = bflo(gq.x) * v0[0]; r[1] = bfhi(gq.x) * v0[1]; r[2] = bflo(gq.y) * v0[2]; r[3] = bfhi(gq.y) * v0[3];
;                         r[4] = bflo(gq.z) * v1[0]; r[5] = bfhi(gq.z) * v1[1]; r[6] = bflo(gq.w) * v1[2]; r[7] = bfhi(gq.w) * v1[3];
;                         if (MODE == 2) { const u32x4 o = *(const u32x4*)(O + off);
;                             r[0] += bflo(o.x); r[1] += bfhi(o.x); r[2] += bflo(o.y); r[3] += bfhi(o.y); r[4] += bflo(o.z); r[5] += bfhi(o.z); r[6] += bflo(o.w); r[7] += bfhi(o.w); } }
;                     u32x4 w; w.x = cvt_pk_bf16(r[0], r[1]); w.y = cvt_pk_bf16(r[2], r[3]); w.z = cvt_pk_bf16(r[4], r[5]); w.w = cvt_pk_bf16(r[6], r[7]);
;                     *(u32x4*)(O + off) = w; } }
.LBB0_1027:
	v_lshl_add_u32 v148, s50, 8, v155
	v_lshl_or_b32 v146, s72, 8, v153
	v_ashrrev_i32_e32 v149, 31, v148
	v_ashrrev_i32_e32 v147, 31, v146
	v_lshlrev_b64 v[144:145], 11, v[148:149]
	v_lshl_add_u64 v[144:145], v[144:145], 0, v[146:147]
	v_lshlrev_b64 v[144:145], 1, v[144:145]
	v_lshl_add_u64 v[158:159], s[28:29], 0, v[144:145]
	v_lshl_add_u64 v[166:167], s[24:25], 0, v[144:145]
	global_load_dwordx4 v[158:161], v[158:159], off nt
	v_or_b32_e32 v168, 0x100, v144
	global_load_dwordx4 v[162:165], v[166:167], off nt
	v_mov_b32_e32 v169, v145
	v_lshl_add_u64 v[170:171], s[28:29], 0, v[168:169]
	s_andn2_b64 vcc, exec, s[0:1]
	s_mov_b64 s[0:1], -1
	s_waitcnt vmcnt(0)
	v_lshlrev_b32_e32 v149, 16, v158
	v_and_b32_e32 v154, 0xffff0000, v158
	v_and_b32_e32 v158, 0xffff0000, v159
	v_lshlrev_b32_e32 v173, 16, v162
	v_and_b32_e32 v162, 0xffff0000, v162
	v_lshlrev_b32_e32 v174, 16, v163
	v_and_b32_e32 v163, 0xffff0000, v163
	v_lshlrev_b32_e32 v157, 16, v159
	v_lshlrev_b32_e32 v159, 16, v160
	v_and_b32_e32 v160, 0xffff0000, v160
	v_lshlrev_b32_e32 v175, 16, v164
	v_and_b32_e32 v164, 0xffff0000, v164
	v_fmac_f32_e32 v162, v125, v154
	v_fmac_f32_e32 v163, v127, v158
	v_lshlrev_b32_e32 v172, 16, v161
	v_and_b32_e32 v161, 0xffff0000, v161
	v_lshlrev_b32_e32 v176, 16, v165
	v_and_b32_e32 v165, 0xffff0000, v165
	v_fmac_f32_e32 v173, v124, v149
	v_fmac_f32_e32 v174, v126, v157
	v_fmac_f32_e32 v175, v120, v159
	v_fmac_f32_e32 v164, v121, v160
	v_cvt_pk_bf16_f32 v120, v173, v162
	v_cvt_pk_bf16_f32 v121, v174, v163
	v_lshl_add_u64 v[162:163], s[24:25], 0, v[168:169]
	v_fmac_f32_e32 v176, v122, v172
	v_fmac_f32_e32 v165, v123, v161
	v_cvt_pk_bf16_f32 v122, v175, v164
	v_cvt_pk_bf16_f32 v123, v176, v165
	global_load_dwordx4 v[124:127], v[170:171], off nt
	global_load_dwordx4 v[158:161], v[162:163], off nt
	v_or_b32_e32 v164, 16, v148
	v_ashrrev_i32_e32 v165, 31, v164
	v_lshlrev_b64 v[164:165], 11, v[164:165]
	v_lshl_add_u64 v[164:165], v[164:165], 0, v[146:147]
	v_lshlrev_b64 v[164:165], 1, v[164:165]
	global_store_dwordx4 v[166:167], v[120:123], off
	v_lshl_add_u64 v[168:169], s[28:29], 0, v[164:165]
	s_waitcnt vmcnt(1)
	v_lshlrev_b32_e32 v149, 16, v158
	v_lshlrev_b32_e32 v120, 16, v124
	v_and_b32_e32 v121, 0xffff0000, v124
	v_lshlrev_b32_e32 v122, 16, v125
	v_and_b32_e32 v123, 0xffff0000, v125
	v_lshlrev_b32_e32 v124, 16, v126
	v_and_b32_e32 v125, 0xffff0000, v126
	v_lshlrev_b32_e32 v126, 16, v127
	v_and_b32_e32 v127, 0xffff0000, v127
	v_and_b32_e32 v154, 0xffff0000, v158
	v_lshlrev_b32_e32 v157, 16, v159
	v_and_b32_e32 v158, 0xffff0000, v159
	v_lshlrev_b32_e32 v159, 16, v160
	v_and_b32_e32 v160, 0xffff0000, v160
	v_lshlrev_b32_e32 v166, 16, v161
	v_and_b32_e32 v161, 0xffff0000, v161
	v_fmac_f32_e32 v149, v116, v120
	v_fmac_f32_e32 v154, v117, v121
	v_fmac_f32_e32 v157, v118, v122
	v_fmac_f32_e32 v158, v119, v123
	v_fmac_f32_e32 v159, v112, v124
	v_fmac_f32_e32 v160, v113, v125
	v_fmac_f32_e32 v166, v114, v126
	v_fmac_f32_e32 v161, v115, v127
	v_cvt_pk_bf16_f32 v112, v149, v154
	v_cvt_pk_bf16_f32 v113, v157, v158
	v_cvt_pk_bf16_f32 v114, v159, v160
	v_cvt_pk_bf16_f32 v115, v166, v161
	global_store_dwordx4 v[162:163], v[112:115], off
	v_lshl_add_u64 v[120:121], s[24:25], 0, v[164:165]
	global_load_dwordx4 v[112:115], v[168:169], off nt
	global_load_dwordx4 v[116:119], v[120:121], off nt
	v_or_b32_e32 v164, 0x100, v164
	v_lshl_add_u64 v[122:123], s[28:29], 0, v[164:165]
	s_waitcnt vmcnt(1)
	v_lshlrev_b32_e32 v124, 16, v112
	v_and_b32_e32 v112, 0xffff0000, v112
	v_lshlrev_b32_e32 v125, 16, v113
	v_and_b32_e32 v113, 0xffff0000, v113
	s_waitcnt vmcnt(0)
	v_lshlrev_b32_e32 v149, 16, v116
	v_and_b32_e32 v116, 0xffff0000, v116
	v_lshlrev_b32_e32 v154, 16, v117
	v_and_b32_e32 v117, 0xffff0000, v117
	v_lshlrev_b32_e32 v126, 16, v114
	v_and_b32_e32 v114, 0xffff0000, v114
	v_lshlrev_b32_e32 v157, 16, v118
	v_and_b32_e32 v118, 0xffff0000, v118
	v_fmac_f32_e32 v116, v109, v112
	v_fmac_f32_e32 v117, v111, v113
	v_lshlrev_b32_e32 v127, 16, v115
	v_and_b32_e32 v115, 0xffff0000, v115
	v_lshlrev_b32_e32 v158, 16, v119
	v_and_b32_e32 v119, 0xffff0000, v119
	v_fmac_f32_e32 v149, v108, v124
	v_fmac_f32_e32 v154, v110, v125
	v_fmac_f32_e32 v157, v104, v126
	v_fmac_f32_e32 v118, v105, v114
	v_cvt_pk_bf16_f32 v104, v149, v116
	v_cvt_pk_bf16_f32 v105, v154, v117
	v_lshl_add_u64 v[116:117], s[24:25], 0, v[164:165]
	v_fmac_f32_e32 v158, v106, v127
	v_fmac_f32_e32 v119, v107, v115
	v_cvt_pk_bf16_f32 v106, v157, v118
	v_cvt_pk_bf16_f32 v107, v158, v119
	global_load_dwordx4 v[108:111], v[122:123], off nt
	global_load_dwordx4 v[112:115], v[116:117], off nt
	v_or_b32_e32 v118, 32, v148
	v_ashrrev_i32_e32 v119, 31, v118
	v_lshlrev_b64 v[118:119], 11, v[118:119]
	v_lshl_add_u64 v[118:119], v[118:119], 0, v[146:147]
	v_lshlrev_b64 v[118:119], 1, v[118:119]
	global_store_dwordx4 v[120:121], v[104:107], off
	v_lshl_add_u64 v[122:123], s[28:29], 0, v[118:119]
	s_waitcnt vmcnt(1)
	v_lshlrev_b32_e32 v120, 16, v112
	v_lshlrev_b32_e32 v104, 16, v108
	v_and_b32_e32 v105, 0xffff0000, v108
	v_lshlrev_b32_e32 v106, 16, v109
	v_and_b32_e32 v107, 0xffff0000, v109
	v_lshlrev_b32_e32 v108, 16, v110
	v_and_b32_e32 v109, 0xffff0000, v110
	v_lshlrev_b32_e32 v110, 16, v111
	v_and_b32_e32 v111, 0xffff0000, v111
	v_and_b32_e32 v112, 0xffff0000, v112
	v_lshlrev_b32_e32 v121, 16, v113
	v_and_b32_e32 v113, 0xffff0000, v113
	v_lshlrev_b32_e32 v124, 16, v114
	v_and_b32_e32 v114, 0xffff0000, v114
	v_lshlrev_b32_e32 v125, 16, v115
	v_and_b32_e32 v115, 0xffff0000, v115
	v_fmac_f32_e32 v120, v100, v104
	v_fmac_f32_e32 v112, v101, v105
	v_fmac_f32_e32 v121, v102, v106
	v_fmac_f32_e32 v113, v103, v107
	v_fmac_f32_e32 v124, v96, v108
	v_fmac_f32_e32 v114, v97, v109
	v_fmac_f32_e32 v125, v98, v110
	v_fmac_f32_e32 v115, v99, v111
	v_cvt_pk_bf16_f32 v96, v120, v112
	v_cvt_pk_bf16_f32 v97, v121, v113
	v_cvt_pk_bf16_f32 v98, v124, v114
	v_cvt_pk_bf16_f32 v99, v125, v115
	global_store_dwordx4 v[116:117], v[96:99], off
	v_lshl_add_u64 v[104:105], s[24:25], 0, v[118:119]
	global_load_dwordx4 v[96:99], v[122:123], off nt
	global_load_dwordx4 v[100:103], v[104:105], off nt
	v_or_b32_e32 v118, 0x100, v118
	v_lshl_add_u64 v[106:107], s[28:29], 0, v[118:119]
	s_waitcnt vmcnt(1)
; __device__ __forceinline__ unsigned cvt_pk_bf16(float lo, float hi) { unsigned r; asm volatile("v_cvt_pk_bf16_f32 %0, %1, %2" : "=v"(r) : "v"(lo), "v"(hi)); return r; }
;     __device__ __forceinline__ void operator()(const f32x4 (&acc)[2][2][4][2], const pg8::Unit& u, int wr, int wc, int fr, int fq) const {
;     ...
;                     else { const u32x4 gq = *(const u32x4*)(G + off);
;                         r[0] = bflo(gq.x) * v0[0]; r[1] = bfhi(gq.x) * v0[1]; r[2] = bflo(gq.y) * v0[2]; r[3] = bfhi(gq.y) * v0[3];
;                         r[4] = bflo(gq.z) * v1[0]; r[5] = bfhi(gq.z) * v1[1]; r[6] = bflo(gq.w) * v1[2]; r[7] = bfhi(gq.w) * v1[3];
;                         if (MODE == 2) { const u32x4 o = *(const u32x4*)(O + off);
;                             r[0] += bflo(o.x); r[1] += bfhi(o.x); r[2] += bflo(o.y); r[3] += bfhi(o.y); r[4] += bflo(o.z); r[5] += bfhi(o.z); r[6] += bflo(o.w); r[7] += bfhi(o.w); } }
;                     u32x4 w; w.x = cvt_pk_bf16(r[0], r[1]); w.y = cvt_pk_bf16(r[2], r[3]); w.z = cvt_pk_bf16(r[4], r[5]); w.w = cvt_pk_bf16(r[6], r[7]);
;                     *(u32x4*)(O + off) = w; } }
	v_lshlrev_b32_e32 v108, 16, v96
	v_and_b32_e32 v96, 0xffff0000, v96
	v_lshlrev_b32_e32 v109, 16, v97
	v_and_b32_e32 v97, 0xffff0000, v97
	s_waitcnt vmcnt(0)
	v_lshlrev_b32_e32 v112, 16, v100
	v_and_b32_e32 v100, 0xffff0000, v100
	v_lshlrev_b32_e32 v113, 16, v101
	v_and_b32_e32 v101, 0xffff0000, v101
	v_lshlrev_b32_e32 v110, 16, v98
	v_and_b32_e32 v98, 0xffff0000, v98
	v_lshlrev_b32_e32 v114, 16, v102
	v_and_b32_e32 v102, 0xffff0000, v102
	v_fmac_f32_e32 v100, v93, v96
	v_fmac_f32_e32 v101, v95, v97
	v_lshlrev_b32_e32 v111, 16, v99
	v_and_b32_e32 v99, 0xffff0000, v99
	v_lshlrev_b32_e32 v115, 16, v103
	v_and_b32_e32 v103, 0xffff0000, v103
	v_fmac_f32_e32 v112, v92, v108
	v_fmac_f32_e32 v113, v94, v109
	v_fmac_f32_e32 v114, v88, v110
	v_fmac_f32_e32 v102, v89, v98
	v_cvt_pk_bf16_f32 v88, v112, v100
	v_cvt_pk_bf16_f32 v89, v113, v101
	v_lshl_add_u64 v[100:101], s[24:25], 0, v[118:119]
	v_fmac_f32_e32 v115, v90, v111
	v_fmac_f32_e32 v103, v91, v99
	v_cvt_pk_bf16_f32 v90, v114, v102
	v_cvt_pk_bf16_f32 v91, v115, v103
	global_load_dwordx4 v[92:95], v[106:107], off nt
	global_load_dwordx4 v[96:99], v[100:101], off nt
	v_or_b32_e32 v102, 48, v148
	v_ashrrev_i32_e32 v103, 31, v102
	v_lshlrev_b64 v[102:103], 11, v[102:103]
	v_lshl_add_u64 v[102:103], v[102:103], 0, v[146:147]
	v_lshlrev_b64 v[102:103], 1, v[102:103]
	global_store_dwordx4 v[104:105], v[88:91], off
	v_lshl_add_u64 v[106:107], s[28:29], 0, v[102:103]
	s_waitcnt vmcnt(1)
	v_lshlrev_b32_e32 v104, 16, v96
	v_lshlrev_b32_e32 v88, 16, v92
	v_and_b32_e32 v89, 0xffff0000, v92
	v_lshlrev_b32_e32 v90, 16, v93
	v_and_b32_e32 v91, 0xffff0000, v93
	v_lshlrev_b32_e32 v92, 16, v94
	v_and_b32_e32 v93, 0xffff0000, v94
	v_lshlrev_b32_e32 v94, 16, v95
	v_and_b32_e32 v95, 0xffff0000, v95
	v_and_b32_e32 v96, 0xffff0000, v96
	v_lshlrev_b32_e32 v105, 16, v97
	v_and_b32_e32 v97, 0xffff0000, v97
	v_lshlrev_b32_e32 v108, 16, v98
	v_and_b32_e32 v98, 0xffff0000, v98
	v_lshlrev_b32_e32 v109, 16, v99
	v_and_b32_e32 v99, 0xffff0000, v99
	v_fmac_f32_e32 v104, v84, v88
	v_fmac_f32_e32 v96, v85, v89
	v_fmac_f32_e32 v105, v86, v90
	v_fmac_f32_e32 v97, v87, v91
	v_fmac_f32_e32 v108, v80, v92
	v_fmac_f32_e32 v98, v81, v93
	v_fmac_f32_e32 v109, v82, v94
	v_fmac_f32_e32 v99, v83, v95
	v_cvt_pk_bf16_f32 v80, v104, v96
	v_cvt_pk_bf16_f32 v81, v105, v97
	v_cvt_pk_bf16_f32 v82, v108, v98
	v_cvt_pk_bf16_f32 v83, v109, v99
	global_store_dwordx4 v[100:101], v[80:83], off
	v_lshl_add_u64 v[88:89], s[24:25], 0, v[102:103]
	global_load_dwordx4 v[80:83], v[106:107], off nt
	global_load_dwordx4 v[84:87], v[88:89], off nt
	v_or_b32_e32 v102, 0x100, v102
	v_lshl_add_u64 v[90:91], s[28:29], 0, v[102:103]
	s_waitcnt vmcnt(1)
	v_lshlrev_b32_e32 v92, 16, v80
	v_and_b32_e32 v80, 0xffff0000, v80
	v_lshlrev_b32_e32 v93, 16, v81
	v_and_b32_e32 v81, 0xffff0000, v81
	s_waitcnt vmcnt(0)
	v_lshlrev_b32_e32 v96, 16, v84
	v_and_b32_e32 v84, 0xffff0000, v84
	v_lshlrev_b32_e32 v97, 16, v85
	v_and_b32_e32 v85, 0xffff0000, v85
	v_lshlrev_b32_e32 v94, 16, v82
	v_and_b32_e32 v82, 0xffff0000, v82
	v_lshlrev_b32_e32 v98, 16, v86
	v_and_b32_e32 v86, 0xffff0000, v86
	v_fmac_f32_e32 v84, v77, v80
	v_fmac_f32_e32 v85, v79, v81
	v_lshlrev_b32_e32 v95, 16, v83
	v_and_b32_e32 v83, 0xffff0000, v83
	v_lshlrev_b32_e32 v99, 16, v87
	v_and_b32_e32 v87, 0xffff0000, v87
	v_fmac_f32_e32 v96, v76, v92
	v_fmac_f32_e32 v97, v78, v93
	v_fmac_f32_e32 v98, v72, v94
	v_fmac_f32_e32 v86, v73, v82
	v_cvt_pk_bf16_f32 v72, v96, v84
	v_cvt_pk_bf16_f32 v73, v97, v85
	v_lshl_add_u64 v[84:85], s[24:25], 0, v[102:103]
	v_fmac_f32_e32 v99, v74, v95
	v_fmac_f32_e32 v87, v75, v83
	v_cvt_pk_bf16_f32 v74, v98, v86
	v_cvt_pk_bf16_f32 v75, v99, v87
	global_load_dwordx4 v[76:79], v[90:91], off nt
	global_load_dwordx4 v[80:83], v[84:85], off nt
	v_lshl_add_u64 v[86:87], v[144:145], 0, s[6:7]
	global_store_dwordx4 v[88:89], v[72:75], off
	v_lshl_add_u64 v[90:91], s[28:29], 0, v[86:87]
	s_waitcnt vmcnt(1)
	v_lshlrev_b32_e32 v88, 16, v80
	v_lshlrev_b32_e32 v72, 16, v76
	v_and_b32_e32 v73, 0xffff0000, v76
	v_lshlrev_b32_e32 v74, 16, v77
	v_and_b32_e32 v75, 0xffff0000, v77
	v_lshlrev_b32_e32 v76, 16, v78
	v_and_b32_e32 v77, 0xffff0000, v78
	v_lshlrev_b32_e32 v78, 16, v79
	v_and_b32_e32 v79, 0xffff0000, v79
	v_and_b32_e32 v80, 0xffff0000, v80
	v_lshlrev_b32_e32 v89, 16, v81
	v_and_b32_e32 v81, 0xffff0000, v81
	v_lshlrev_b32_e32 v92, 16, v82
	v_and_b32_e32 v82, 0xffff0000, v82
	v_lshlrev_b32_e32 v93, 16, v83
	v_and_b32_e32 v83, 0xffff0000, v83
	v_fmac_f32_e32 v88, v68, v72
	v_fmac_f32_e32 v80, v69, v73
	v_fmac_f32_e32 v89, v70, v74
	v_fmac_f32_e32 v81, v71, v75
	v_fmac_f32_e32 v92, v64, v76
	v_fmac_f32_e32 v82, v65, v77
	v_fmac_f32_e32 v93, v66, v78
	v_fmac_f32_e32 v83, v67, v79
	v_cvt_pk_bf16_f32 v64, v88, v80
	v_cvt_pk_bf16_f32 v65, v89, v81
	v_cvt_pk_bf16_f32 v66, v92, v82
	v_cvt_pk_bf16_f32 v67, v93, v83
	global_store_dwordx4 v[84:85], v[64:67], off
	v_lshl_add_u64 v[72:73], s[24:25], 0, v[86:87]
	global_load_dwordx4 v[64:67], v[90:91], off nt
	global_load_dwordx4 v[68:71], v[72:73], off nt
	v_lshl_add_u64 v[74:75], v[144:145], 0, s[14:15]
	v_lshl_add_u64 v[76:77], s[28:29], 0, v[74:75]
	s_waitcnt vmcnt(1)
	v_lshlrev_b32_e32 v78, 16, v64
	v_and_b32_e32 v64, 0xffff0000, v64
	v_lshlrev_b32_e32 v79, 16, v65
	v_and_b32_e32 v65, 0xffff0000, v65
	s_waitcnt vmcnt(0)
; __device__ __forceinline__ unsigned cvt_pk_bf16(float lo, float hi) { unsigned r; asm volatile("v_cvt_pk_bf16_f32 %0, %1, %2" : "=v"(r) : "v"(lo), "v"(hi)); return r; }
;     __device__ __forceinline__ void operator()(const f32x4 (&acc)[2][2][4][2], const pg8::Unit& u, int wr, int wc, int fr, int fq) const {
;     ...
;                     else { const u32x4 gq = *(const u32x4*)(G + off);
;                         r[0] = bflo(gq.x) * v0[0]; r[1] = bfhi(gq.x) * v0[1]; r[2] = bflo(gq.y) * v0[2]; r[3] = bfhi(gq.y) * v0[3];
;                         r[4] = bflo(gq.z) * v1[0]; r[5] = bfhi(gq.z) * v1[1]; r[6] = bflo(gq.w) * v1[2]; r[7] = bfhi(gq.w) * v1[3];
;                         if (MODE == 2) { const u32x4 o = *(const u32x4*)(O + off);
;                             r[0] += bflo(o.x); r[1] += bfhi(o.x); r[2] += bflo(o.y); r[3] += bfhi(o.y); r[4] += bflo(o.z); r[5] += bfhi(o.z); r[6] += bflo(o.w); r[7] += bfhi(o.w); } }
;                     u32x4 w; w.x = cvt_pk_bf16(r[0], r[1]); w.y = cvt_pk_bf16(r[2], r[3]); w.z = cvt_pk_bf16(r[4], r[5]); w.w = cvt_pk_bf16(r[6], r[7]);
;                     *(u32x4*)(O + off) = w; } }
	v_lshlrev_b32_e32 v82, 16, v68
	v_and_b32_e32 v68, 0xffff0000, v68
	v_lshlrev_b32_e32 v83, 16, v69
	v_and_b32_e32 v69, 0xffff0000, v69
	v_lshlrev_b32_e32 v80, 16, v66
	v_and_b32_e32 v66, 0xffff0000, v66
	v_lshlrev_b32_e32 v84, 16, v70
	v_and_b32_e32 v70, 0xffff0000, v70
	v_fmac_f32_e32 v68, v61, v64
	v_fmac_f32_e32 v69, v63, v65
	v_lshlrev_b32_e32 v81, 16, v67
	v_and_b32_e32 v67, 0xffff0000, v67
	v_lshlrev_b32_e32 v85, 16, v71
	v_and_b32_e32 v71, 0xffff0000, v71
	v_fmac_f32_e32 v82, v60, v78
	v_fmac_f32_e32 v83, v62, v79
	v_fmac_f32_e32 v84, v56, v80
	v_fmac_f32_e32 v70, v57, v66
	v_cvt_pk_bf16_f32 v56, v82, v68
	v_cvt_pk_bf16_f32 v57, v83, v69
	v_lshl_add_u64 v[68:69], s[24:25], 0, v[74:75]
	v_fmac_f32_e32 v85, v58, v81
	v_fmac_f32_e32 v71, v59, v67
	v_cvt_pk_bf16_f32 v58, v84, v70
	v_cvt_pk_bf16_f32 v59, v85, v71
	global_load_dwordx4 v[60:63], v[76:77], off nt
	global_load_dwordx4 v[64:67], v[68:69], off nt
	v_lshl_add_u64 v[70:71], v[144:145], 0, s[16:17]
	global_store_dwordx4 v[72:73], v[56:59], off
	v_lshl_add_u64 v[74:75], s[28:29], 0, v[70:71]
	s_waitcnt vmcnt(1)
	v_lshlrev_b32_e32 v72, 16, v64
	v_lshlrev_b32_e32 v56, 16, v60
	v_and_b32_e32 v57, 0xffff0000, v60
	v_lshlrev_b32_e32 v58, 16, v61
	v_and_b32_e32 v59, 0xffff0000, v61
	v_lshlrev_b32_e32 v60, 16, v62
	v_and_b32_e32 v61, 0xffff0000, v62
	v_lshlrev_b32_e32 v62, 16, v63
	v_and_b32_e32 v63, 0xffff0000, v63
	v_and_b32_e32 v64, 0xffff0000, v64
	v_lshlrev_b32_e32 v73, 16, v65
	v_and_b32_e32 v65, 0xffff0000, v65
	v_lshlrev_b32_e32 v76, 16, v66
	v_and_b32_e32 v66, 0xffff0000, v66
	v_lshlrev_b32_e32 v77, 16, v67
	v_and_b32_e32 v67, 0xffff0000, v67
	v_fmac_f32_e32 v72, v52, v56
	v_fmac_f32_e32 v64, v53, v57
	v_fmac_f32_e32 v73, v54, v58
	v_fmac_f32_e32 v65, v55, v59
	v_fmac_f32_e32 v76, v48, v60
	v_fmac_f32_e32 v66, v49, v61
	v_fmac_f32_e32 v77, v50, v62
	v_fmac_f32_e32 v67, v51, v63
	v_cvt_pk_bf16_f32 v48, v72, v64
	v_cvt_pk_bf16_f32 v49, v73, v65
	v_cvt_pk_bf16_f32 v50, v76, v66
	v_cvt_pk_bf16_f32 v51, v77, v67
	global_store_dwordx4 v[68:69], v[48:51], off
	v_lshl_add_u64 v[56:57], s[24:25], 0, v[70:71]
	global_load_dwordx4 v[48:51], v[74:75], off nt
	global_load_dwordx4 v[52:55], v[56:57], off nt
	v_lshl_add_u64 v[58:59], v[144:145], 0, s[18:19]
	v_lshl_add_u64 v[60:61], s[28:29], 0, v[58:59]
	s_waitcnt vmcnt(1)
	v_lshlrev_b32_e32 v62, 16, v48
	v_and_b32_e32 v48, 0xffff0000, v48
	v_lshlrev_b32_e32 v63, 16, v49
	v_and_b32_e32 v49, 0xffff0000, v49
	s_waitcnt vmcnt(0)
	v_lshlrev_b32_e32 v66, 16, v52
	v_and_b32_e32 v52, 0xffff0000, v52
	v_lshlrev_b32_e32 v67, 16, v53
	v_and_b32_e32 v53, 0xffff0000, v53
	v_lshlrev_b32_e32 v64, 16, v50
	v_and_b32_e32 v50, 0xffff0000, v50
	v_lshlrev_b32_e32 v68, 16, v54
	v_and_b32_e32 v54, 0xffff0000, v54
	v_fmac_f32_e32 v52, v45, v48
	v_fmac_f32_e32 v53, v47, v49
	v_lshlrev_b32_e32 v65, 16, v51
	v_and_b32_e32 v51, 0xffff0000, v51
	v_lshlrev_b32_e32 v69, 16, v55
	v_and_b32_e32 v55, 0xffff0000, v55
	v_fmac_f32_e32 v66, v44, v62
	v_fmac_f32_e32 v67, v46, v63
	v_fmac_f32_e32 v68, v40, v64
	v_fmac_f32_e32 v54, v41, v50
	v_cvt_pk_bf16_f32 v40, v66, v52
	v_cvt_pk_bf16_f32 v41, v67, v53
	v_lshl_add_u64 v[52:53], s[24:25], 0, v[58:59]
	v_fmac_f32_e32 v69, v42, v65
	v_fmac_f32_e32 v55, v43, v51
	v_cvt_pk_bf16_f32 v42, v68, v54
	v_cvt_pk_bf16_f32 v43, v69, v55
	global_load_dwordx4 v[44:47], v[60:61], off nt
	global_load_dwordx4 v[48:51], v[52:53], off nt
	v_lshl_add_u64 v[54:55], v[144:145], 0, s[20:21]
	global_store_dwordx4 v[56:57], v[40:43], off
	v_lshl_add_u64 v[58:59], s[28:29], 0, v[54:55]
	s_waitcnt vmcnt(1)
	v_lshlrev_b32_e32 v56, 16, v48
	v_lshlrev_b32_e32 v40, 16, v44
	v_and_b32_e32 v41, 0xffff0000, v44
	v_lshlrev_b32_e32 v42, 16, v45
	v_and_b32_e32 v43, 0xffff0000, v45
	v_lshlrev_b32_e32 v44, 16, v46
	v_and_b32_e32 v45, 0xffff0000, v46
	v_lshlrev_b32_e32 v46, 16, v47
	v_and_b32_e32 v47, 0xffff0000, v47
	v_and_b32_e32 v48, 0xffff0000, v48
	v_lshlrev_b32_e32 v57, 16, v49
	v_and_b32_e32 v49, 0xffff0000, v49
	v_lshlrev_b32_e32 v60, 16, v50
	v_and_b32_e32 v50, 0xffff0000, v50
	v_lshlrev_b32_e32 v61, 16, v51
	v_and_b32_e32 v51, 0xffff0000, v51
	v_fmac_f32_e32 v56, v36, v40
	v_fmac_f32_e32 v48, v37, v41
	v_fmac_f32_e32 v57, v38, v42
	v_fmac_f32_e32 v49, v39, v43
	v_fmac_f32_e32 v60, v32, v44
	v_fmac_f32_e32 v50, v33, v45
	v_fmac_f32_e32 v61, v34, v46
	v_fmac_f32_e32 v51, v35, v47
	v_cvt_pk_bf16_f32 v32, v56, v48
	v_cvt_pk_bf16_f32 v33, v57, v49
	v_cvt_pk_bf16_f32 v34, v60, v50
	v_cvt_pk_bf16_f32 v35, v61, v51
	global_store_dwordx4 v[52:53], v[32:35], off
	v_lshl_add_u64 v[40:41], s[24:25], 0, v[54:55]
	global_load_dwordx4 v[32:35], v[58:59], off nt
	global_load_dwordx4 v[36:39], v[40:41], off nt
	v_lshl_add_u64 v[42:43], v[144:145], 0, s[22:23]
	v_lshl_add_u64 v[44:45], s[28:29], 0, v[42:43]
	s_waitcnt vmcnt(1)
; __device__ __forceinline__ unsigned cvt_pk_bf16(float lo, float hi) { unsigned r; asm volatile("v_cvt_pk_bf16_f32 %0, %1, %2" : "=v"(r) : "v"(lo), "v"(hi)); return r; }
;     __device__ __forceinline__ void operator()(const f32x4 (&acc)[2][2][4][2], const pg8::Unit& u, int wr, int wc, int fr, int fq) const {
;     ...
;                     else { const u32x4 gq = *(const u32x4*)(G + off);
;                         r[0] = bflo(gq.x) * v0[0]; r[1] = bfhi(gq.x) * v0[1]; r[2] = bflo(gq.y) * v0[2]; r[3] = bfhi(gq.y) * v0[3];
;                         r[4] = bflo(gq.z) * v1[0]; r[5] = bfhi(gq.z) * v1[1]; r[6] = bflo(gq.w) * v1[2]; r[7] = bfhi(gq.w) * v1[3];
;                         if (MODE == 2) { const u32x4 o = *(const u32x4*)(O + off);
;                             r[0] += bflo(o.x); r[1] += bfhi(o.x); r[2] += bflo(o.y); r[3] += bfhi(o.y); r[4] += bflo(o.z); r[5] += bfhi(o.z); r[6] += bflo(o.w); r[7] += bfhi(o.w); } }
;                     u32x4 w; w.x = cvt_pk_bf16(r[0], r[1]); w.y = cvt_pk_bf16(r[2], r[3]); w.z = cvt_pk_bf16(r[4], r[5]); w.w = cvt_pk_bf16(r[6], r[7]);
;                     *(u32x4*)(O + off) = w; } }
	v_lshlrev_b32_e32 v46, 16, v32
	v_and_b32_e32 v32, 0xffff0000, v32
	v_lshlrev_b32_e32 v47, 16, v33
	v_and_b32_e32 v33, 0xffff0000, v33
	s_waitcnt vmcnt(0)
	v_lshlrev_b32_e32 v50, 16, v36
	v_and_b32_e32 v36, 0xffff0000, v36
	v_lshlrev_b32_e32 v51, 16, v37
	v_and_b32_e32 v37, 0xffff0000, v37
	v_lshlrev_b32_e32 v48, 16, v34
	v_and_b32_e32 v34, 0xffff0000, v34
	v_lshlrev_b32_e32 v52, 16, v38
	v_and_b32_e32 v38, 0xffff0000, v38
	v_fmac_f32_e32 v36, v29, v32
	v_fmac_f32_e32 v37, v31, v33
	v_lshlrev_b32_e32 v49, 16, v35
	v_and_b32_e32 v35, 0xffff0000, v35
	v_lshlrev_b32_e32 v53, 16, v39
	v_and_b32_e32 v39, 0xffff0000, v39
	v_fmac_f32_e32 v50, v28, v46
	v_fmac_f32_e32 v51, v30, v47
	v_fmac_f32_e32 v52, v24, v48
	v_fmac_f32_e32 v38, v25, v34
	v_cvt_pk_bf16_f32 v24, v50, v36
	v_cvt_pk_bf16_f32 v25, v51, v37
	v_lshl_add_u64 v[36:37], s[24:25], 0, v[42:43]
	v_fmac_f32_e32 v53, v26, v49
	v_fmac_f32_e32 v39, v27, v35
	v_cvt_pk_bf16_f32 v26, v52, v38
	v_cvt_pk_bf16_f32 v27, v53, v39
	global_load_dwordx4 v[28:31], v[44:45], off nt
	global_load_dwordx4 v[32:35], v[36:37], off nt
	v_lshl_add_u64 v[38:39], v[144:145], 0, s[38:39]
	global_store_dwordx4 v[40:41], v[24:27], off
	v_lshl_add_u64 v[42:43], s[28:29], 0, v[38:39]
	s_waitcnt vmcnt(1)
	v_lshlrev_b32_e32 v40, 16, v32
	v_lshlrev_b32_e32 v24, 16, v28
	v_and_b32_e32 v25, 0xffff0000, v28
	v_lshlrev_b32_e32 v26, 16, v29
	v_and_b32_e32 v27, 0xffff0000, v29
	v_lshlrev_b32_e32 v28, 16, v30
	v_and_b32_e32 v29, 0xffff0000, v30
	v_lshlrev_b32_e32 v30, 16, v31
	v_and_b32_e32 v31, 0xffff0000, v31
	v_and_b32_e32 v32, 0xffff0000, v32
	v_lshlrev_b32_e32 v41, 16, v33
	v_and_b32_e32 v33, 0xffff0000, v33
	v_lshlrev_b32_e32 v44, 16, v34
	v_and_b32_e32 v34, 0xffff0000, v34
	v_lshlrev_b32_e32 v45, 16, v35
	v_and_b32_e32 v35, 0xffff0000, v35
	v_fmac_f32_e32 v40, v20, v24
	v_fmac_f32_e32 v32, v21, v25
	v_fmac_f32_e32 v41, v22, v26
	v_fmac_f32_e32 v33, v23, v27
	v_fmac_f32_e32 v44, v16, v28
	v_fmac_f32_e32 v34, v17, v29
	v_fmac_f32_e32 v45, v18, v30
	v_fmac_f32_e32 v35, v19, v31
	v_cvt_pk_bf16_f32 v16, v40, v32
	v_cvt_pk_bf16_f32 v17, v41, v33
	v_cvt_pk_bf16_f32 v18, v44, v34
	v_cvt_pk_bf16_f32 v19, v45, v35
	global_store_dwordx4 v[36:37], v[16:19], off
	v_lshl_add_u64 v[24:25], s[24:25], 0, v[38:39]
	global_load_dwordx4 v[16:19], v[42:43], off nt
	global_load_dwordx4 v[20:23], v[24:25], off nt
	v_lshl_add_u64 v[26:27], v[144:145], 0, s[40:41]
	v_lshl_add_u64 v[28:29], s[28:29], 0, v[26:27]
	s_waitcnt vmcnt(1)
	v_lshlrev_b32_e32 v30, 16, v16
	v_and_b32_e32 v16, 0xffff0000, v16
	v_lshlrev_b32_e32 v31, 16, v17
	v_and_b32_e32 v17, 0xffff0000, v17
	s_waitcnt vmcnt(0)
	v_lshlrev_b32_e32 v34, 16, v20
	v_and_b32_e32 v20, 0xffff0000, v20
	v_lshlrev_b32_e32 v35, 16, v21
	v_and_b32_e32 v21, 0xffff0000, v21
	v_lshlrev_b32_e32 v32, 16, v18
	v_and_b32_e32 v18, 0xffff0000, v18
	v_lshlrev_b32_e32 v36, 16, v22
	v_and_b32_e32 v22, 0xffff0000, v22
	v_fmac_f32_e32 v20, v13, v16
	v_fmac_f32_e32 v21, v15, v17
	v_lshlrev_b32_e32 v33, 16, v19
	v_and_b32_e32 v19, 0xffff0000, v19
	v_lshlrev_b32_e32 v37, 16, v23
	v_and_b32_e32 v23, 0xffff0000, v23
	v_fmac_f32_e32 v34, v12, v30
	v_fmac_f32_e32 v35, v14, v31
	v_fmac_f32_e32 v36, v8, v32
	v_fmac_f32_e32 v22, v9, v18
	v_cvt_pk_bf16_f32 v8, v34, v20
	v_cvt_pk_bf16_f32 v9, v35, v21
	v_lshl_add_u64 v[20:21], s[24:25], 0, v[26:27]
	v_fmac_f32_e32 v37, v10, v33
	v_fmac_f32_e32 v23, v11, v19
	v_cvt_pk_bf16_f32 v10, v36, v22
	v_cvt_pk_bf16_f32 v11, v37, v23
	global_load_dwordx4 v[12:15], v[28:29], off nt
	global_load_dwordx4 v[16:19], v[20:21], off nt
	s_waitcnt vmcnt(0)
	v_lshlrev_b32_e32 v22, 16, v16
	global_store_dwordx4 v[24:25], v[8:11], off
	v_and_b32_e32 v16, 0xffff0000, v16
	v_lshlrev_b32_e32 v23, 16, v17
	v_lshlrev_b32_e32 v8, 16, v12
	v_and_b32_e32 v9, 0xffff0000, v12
	v_lshlrev_b32_e32 v10, 16, v13
	v_and_b32_e32 v11, 0xffff0000, v13
	v_lshlrev_b32_e32 v12, 16, v14
	v_and_b32_e32 v13, 0xffff0000, v14
	v_lshlrev_b32_e32 v14, 16, v15
	v_and_b32_e32 v15, 0xffff0000, v15
	v_and_b32_e32 v17, 0xffff0000, v17
	v_lshlrev_b32_e32 v24, 16, v18
	v_and_b32_e32 v18, 0xffff0000, v18
	v_lshlrev_b32_e32 v25, 16, v19
	v_and_b32_e32 v19, 0xffff0000, v19
	v_fmac_f32_e32 v22, v4, v8
	v_fmac_f32_e32 v16, v5, v9
	v_fmac_f32_e32 v23, v6, v10
	v_fmac_f32_e32 v17, v7, v11
	v_fmac_f32_e32 v24, v0, v12
	v_fmac_f32_e32 v18, v1, v13
	v_fmac_f32_e32 v25, v2, v14
	v_fmac_f32_e32 v19, v3, v15
	v_cvt_pk_bf16_f32 v0, v22, v16
	v_cvt_pk_bf16_f32 v1, v23, v17
	v_cvt_pk_bf16_f32 v2, v24, v18
	v_cvt_pk_bf16_f32 v3, v25, v19
	global_store_dwordx4 v[20:21], v[0:3], off
	s_cbranch_vccnz .LBB0_1016
	s_andn2_b64 vcc, exec, s[8:9]
	s_cbranch_vccnz .LBB0_1015
	s_barrier
	s_branch .LBB0_1015
